# v8 + scan tasks permuted so that the column slices of one head run on workgroups of the same XCD (shared chunk operands served by one L2)
# speedup vs baseline: 1.0115x; 1.0007x over previous
; #define REP(k) for (int rep_ = 0; rep_ < 1 + ((PROBE_MASK >> (k)) & 1); ++rep_)
; __global__ void __launch_bounds__(512, 2) mega(Args a) {
;     ...
;             const bool scan_block = bx < nsb;
;             if (scan_block && wave < nrole) {
;                 REP(13) for (int id = bx; id < 128; id += G) {
;                     if (tid_p < 16) {}
;                     if (wave == 0) {
;                         if (id < 64) gla_scan_task(p, l, id >> 5, (id >> 3) & 3, id & 7, lds, lane);
;                         else delta_scan_task(p, l, (id - 64) >> 5, ((id - 64) >> 2) & 7, (id - 64) & 3, lds, lane);
;                     } else scan_loader(p, id, wave - 1, lds, lane);
;                 }
.LBB0_1422:
	s_and_b64 vcc, exec, s[0:1]
	s_cbranch_vccz .LBB0_1558
	v_readlane_b32 s0, v254, 63
	s_lshl_b32 s0, s0, 3
	s_cmp_gt_u32 s92, 63
	v_readlane_b32 s1, v248, 0
	v_writelane_b32 v248, s0, 4
	s_cselect_b64 s[24:25], -1, 0
	s_add_i32 s0, s55, -1
	s_cmp_gt_i32 s55, 2
	s_cselect_b64 s[38:39], -1, 0
	s_cmp_lt_i32 s55, 3
	s_cselect_b32 s1, 12, 16
	s_add_i32 s17, s1, 0
	s_lshl_b32 s1, s0, 12
	s_lshl_b32 s4, s0, 5
	s_add_i32 s19, s1, 0
	s_ashr_i32 s5, s4, 31
	s_lshl_b32 s18, s0, 13
	s_add_i32 s20, s19, 0xcc00
	s_cmp_eq_u32 s0, 0
	v_and_b32_e32 v138, 31, v178
	s_cselect_b64 s[0:1], -1, 0
	s_lshl_b32 s6, s55, 2
	v_readlane_b32 s60, v250, 62
	v_or_b32_e32 v144, s4, v138
	v_mov_b32_e32 v145, s5
	s_add_i32 s21, s19, 0x9c00
	s_add_i32 s22, s6, 0
	s_lshl_b64 s[4:5], s[4:5], 2
	v_readlane_b32 s70, v251, 8
	v_lshrrev_b32_e32 v2, 5, v161
	v_readlane_b32 s71, v251, 9
	s_add_u32 s4, s70, s4
	s_movk_i32 s6, 0x110
	v_lshlrev_b32_e32 v3, 4, v161
	v_readlane_b32 s8, v249, 0
	v_lshlrev_b32_e32 v142, 7, v138
	v_mov_b32_e32 v143, v163
	v_writelane_b32 v248, s0, 2
	v_readlane_b32 s61, v250, 63
	v_readlane_b32 s62, v251, 0
	v_readlane_b32 s63, v251, 1
	v_readlane_b32 s64, v251, 2
	v_readlane_b32 s65, v251, 3
	v_readlane_b32 s66, v251, 4
	v_readlane_b32 s67, v251, 5
	v_readlane_b32 s68, v251, 6
	v_readlane_b32 s69, v251, 7
	v_readlane_b32 s72, v251, 10
	v_readlane_b32 s73, v251, 11
	v_readlane_b32 s74, v251, 12
	v_readlane_b32 s75, v251, 13
	s_addc_u32 s5, s71, s5
	v_mad_u32_u24 v194, v138, s6, 0
	v_lshlrev_b32_e32 v148, 4, v2
	v_add_u32_e32 v209, 0, v3
	v_readlane_b32 s9, v249, 1
	v_readlane_b32 s10, v249, 2
	v_readlane_b32 s11, v249, 3
	v_mov_b32_e32 v149, v163
	v_lshlrev_b32_e32 v140, 3, v2
	v_lshlrev_b32_e32 v1, 2, v2
	v_writelane_b32 v248, s1, 3
	v_cmp_eq_u32_e64 s[0:1], 0, v161
	v_lshlrev_b64 v[146:147], 7, v[144:145]
	v_lshlrev_b32_e32 v139, 8, v138
	v_lshlrev_b32_e32 v141, 3, v161
	v_sub_u32_e32 v195, v194, v142
	v_add_u32_e32 v210, 0xe000, v209
	v_lshlrev_b32_e32 v211, 14, v2
	v_lshlrev_b32_e32 v150, 11, v2
	v_mov_b32_e32 v151, v163
	v_lshlrev_b32_e32 v152, 12, v2
	v_mov_b32_e32 v153, v163
	v_lshl_add_u64 v[154:155], s[8:9], 0, v[142:143]
	v_lshl_add_u64 v[156:157], s[10:11], 0, v[142:143]
	v_lshl_add_u64 v[158:159], s[62:63], 0, v[142:143]
	v_lshl_add_u64 v[160:161], s[68:69], 0, v[148:149]
	v_lshl_add_u64 v[178:179], s[72:73], 0, v[148:149]
	v_lshl_add_u64 v[180:181], s[74:75], 0, v[148:149]
	v_lshl_add_u64 v[182:183], s[4:5], 0, v[148:149]
	v_lshl_add_u64 v[184:185], s[64:65], 0, v[148:149]
	v_lshl_add_u64 v[186:187], s[60:61], 0, v[148:149]
	v_lshl_add_u64 v[188:189], s[66:67], 0, v[148:149]
	s_add_i32 s23, s19, 0xc400
	s_add_i32 s36, s19, 0xc800
	s_mov_b32 s37, s30
	s_cmp_gt_u32 s30, 127
	s_cbranch_scc1 .Lscanperm_done
	s_and_b32 s100, s30, 7
	s_lshl_b32 s100, s100, 3
	s_bfe_u32 s37, s30, 0x30003
	s_or_b32 s37, s37, s100
	s_cmp_lt_u32 s30, 64
	s_cbranch_scc1 .Lscanperm_done
	s_sub_u32 s100, s30, 64
	s_and_b32 s37, s100, 15
	s_lshl_b32 s37, s37, 2
	s_lshr_b32 s100, s100, 4
	s_or_b32 s37, s37, s100
	s_add_u32 s37, s37, 64
.Lscanperm_done:
	v_readlane_b32 s41, v252, 4
	v_readlane_b32 s60, v252, 5
	v_readlane_b32 s61, v252, 6
	v_readlane_b32 s62, v252, 7
	v_readlane_b32 s12, v249, 4
	v_readlane_b32 s13, v249, 5
	v_readlane_b32 s14, v249, 6
	v_readlane_b32 s15, v249, 7
	s_branch .LBB0_1444
